# attention->out-proj grid barrier replaced by per-row-panel counters: write-through unit outputs, deferred per-unit completion posts, out-proj waits for the 16 units of its own panel
# speedup vs baseline: 1.0267x; 1.0049x over previous
.LBB0_898:
	v_readlane_b32 s92, v252, 6
	v_cvt_pk_bf16_f32 v1, v2, v3
	v_readlane_b32 s93, v252, 7
	s_waitcnt vmcnt(0)
	global_store_dwordx2 v[66:67], v[0:1], off offset:112 sc1

.LBB0_917:
	v_and_b32_e32 v35, 64, v197
	v_xor_b32_e32 v34, 32, v197
	v_add_u32_e32 v35, 64, v35
	v_cmp_lt_i32_e32 vcc, v34, v35
	s_mov_b64 s[0:1], s[40:41]
	v_lshlrev_b64 v[32:33], 11, v[132:133]
	v_cndmask_b32_e32 v34, v197, v34, vcc
	v_lshlrev_b32_e32 v34, 2, v34
	ds_bpermute_b32 v34, v34, v131
	v_lshl_add_u64 v[32:33], s[0:1], 0, v[32:33]
	v_readlane_b32 s0, v254, 43
	v_readlane_b32 s1, v254, 44
	s_mov_b32 s5, s1
	v_writelane_b32 v254, s0, 43
	s_waitcnt lgkmcnt(0)
	v_add_f32_e32 v34, v131, v34
	s_lshl_b32 s4, s6, 7
	v_writelane_b32 v254, s1, 44
	v_div_scale_f32 v35, s[0:1], v34, v34, 1.0
	v_rcp_f32_e32 v36, v35
	v_lshl_add_u64 v[32:33], v[32:33], 0, s[4:5]
	v_lshlrev_b32_e32 v64, 1, v130
	v_lshl_add_u64 v[32:33], v[32:33], 0, v[64:65]
	v_fma_f32 v37, -v35, v36, 1.0
	v_fmac_f32_e32 v36, v37, v36
	v_div_scale_f32 v37, vcc, 1.0, v34, 1.0
	v_mul_f32_e32 v38, v37, v36
	v_fma_f32 v39, -v35, v38, v37
	v_fmac_f32_e32 v38, v39, v36
	v_fma_f32 v35, -v35, v38, v37
	v_div_fmas_f32 v35, v35, v36, v38
	v_div_fixup_f32 v34, v35, v34, 1.0
	s_mov_b64 s[0:1], 0x6000500
	s_waitcnt vmcnt(0)
	v_lshl_add_u64 v[66:67], v[32:33], 0, s[0:1]
	v_pk_mul_f32 v[16:17], v[16:17], v[34:35] op_sel_hi:[1,0]
	v_pk_mul_f32 v[18:19], v[18:19], v[34:35] op_sel_hi:[1,0]
	s_mov_b32 s0, 0x6000000
	v_cvt_pk_bf16_f32 v16, v16, v17
	v_cvt_pk_bf16_f32 v17, v18, v19
	v_add_co_u32_e32 v18, vcc, s0, v32
	v_pk_mul_f32 v[0:1], v[0:1], v[34:35] op_sel_hi:[1,0]
	s_nop 0
	v_addc_co_u32_e32 v19, vcc, 0, v33, vcc
	v_pk_mul_f32 v[2:3], v[2:3], v[34:35] op_sel_hi:[1,0]
	global_store_dwordx2 v[18:19], v[16:17], off offset:1280 sc1
	v_pk_mul_f32 v[16:17], v[20:21], v[34:35] op_sel_hi:[1,0]
	v_pk_mul_f32 v[18:19], v[22:23], v[34:35] op_sel_hi:[1,0]
	v_cvt_pk_bf16_f32 v0, v0, v1
	v_cvt_pk_bf16_f32 v1, v2, v3
	v_cvt_pk_bf16_f32 v16, v16, v17
	v_cvt_pk_bf16_f32 v17, v18, v19
	global_store_dwordx2 v[66:67], v[0:1], off offset:64 sc1
	v_pk_mul_f32 v[0:1], v[4:5], v[34:35] op_sel_hi:[1,0]
	v_pk_mul_f32 v[2:3], v[6:7], v[34:35] op_sel_hi:[1,0]
	global_store_dwordx2 v[66:67], v[16:17], off offset:16 sc1
	v_pk_mul_f32 v[16:17], v[24:25], v[34:35] op_sel_hi:[1,0]
	v_pk_mul_f32 v[18:19], v[26:27], v[34:35] op_sel_hi:[1,0]
	v_cvt_pk_bf16_f32 v0, v0, v1
	v_cvt_pk_bf16_f32 v1, v2, v3
	v_cvt_pk_bf16_f32 v16, v16, v17
	v_cvt_pk_bf16_f32 v17, v18, v19
	global_store_dwordx2 v[66:67], v[0:1], off offset:80 sc1
	v_pk_mul_f32 v[0:1], v[8:9], v[34:35] op_sel_hi:[1,0]
	v_pk_mul_f32 v[2:3], v[10:11], v[34:35] op_sel_hi:[1,0]
	global_store_dwordx2 v[66:67], v[16:17], off offset:32 sc1
	v_pk_mul_f32 v[16:17], v[28:29], v[34:35] op_sel_hi:[1,0]
	v_pk_mul_f32 v[18:19], v[30:31], v[34:35] op_sel_hi:[1,0]
	v_cvt_pk_bf16_f32 v0, v0, v1
	v_cvt_pk_bf16_f32 v1, v2, v3
	v_cvt_pk_bf16_f32 v16, v16, v17
	v_cvt_pk_bf16_f32 v17, v18, v19
	global_store_dwordx2 v[66:67], v[0:1], off offset:96 sc1
	v_pk_mul_f32 v[0:1], v[12:13], v[34:35] op_sel_hi:[1,0]
	global_store_dwordx2 v[66:67], v[16:17], off offset:48 sc1
	v_cvt_pk_bf16_f32 v0, v0, v1
	v_pk_mul_f32 v[2:3], v[14:15], v[34:35] op_sel_hi:[1,0]
	s_mov_b64 s[0:1], 0

.LBB0_953:
	v_xor_b32_e32 v2, 32, v197
	v_add_u32_e32 v3, 64, v131
	v_cmp_lt_i32_e32 vcc, v2, v3
	v_lshl_add_u32 v0, s69, 11, v130
	s_mov_b64 s[0:1], s[40:41]
	v_cndmask_b32_e32 v2, v197, v2, vcc
	v_lshlrev_b32_e32 v2, 2, v2
	ds_bpermute_b32 v2, v2, v140
	v_ashrrev_i32_e32 v1, 31, v0
	v_lshlrev_b64 v[0:1], 11, v[0:1]
	v_lshl_add_u64 v[0:1], s[0:1], 0, v[0:1]
	s_mov_b32 s1, s29
	v_writelane_b32 v254, s0, 43
	s_waitcnt lgkmcnt(0)
	v_add_f32_e32 v2, v140, v2
	s_lshl_b32 s28, s68, 7
	v_writelane_b32 v254, s1, 44
	v_div_scale_f32 v3, s[0:1], v2, v2, 1.0
	v_rcp_f32_e32 v4, v3
	v_lshl_add_u64 v[0:1], v[0:1], 0, s[28:29]
	v_lshlrev_b32_e32 v64, 1, v133
	v_lshl_add_u64 v[0:1], v[0:1], 0, v[64:65]
	v_fma_f32 v5, -v3, v4, 1.0
	v_fmac_f32_e32 v4, v5, v4
	v_div_scale_f32 v5, vcc, 1.0, v2, 1.0
	v_mul_f32_e32 v6, v5, v4
	v_fma_f32 v7, -v3, v6, v5
	v_fmac_f32_e32 v6, v7, v4
	v_fma_f32 v3, -v3, v6, v5
	v_div_fmas_f32 v3, v3, v4, v6
	s_mov_b64 s[0:1], 0x6000000
	v_div_fixup_f32 v2, v3, v2, 1.0
	v_lshl_add_u64 v[66:67], v[0:1], 0, s[0:1]
	s_mov_b32 s0, 0x6000000
	v_pk_mul_f32 v[4:5], v[32:33], v[2:3] op_sel_hi:[1,0]
	v_pk_mul_f32 v[6:7], v[34:35], v[2:3] op_sel_hi:[1,0]
	v_add_co_u32_e32 v0, vcc, s0, v0
	v_cvt_pk_bf16_f32 v4, v4, v5
	v_cvt_pk_bf16_f32 v5, v6, v7
	v_addc_co_u32_e32 v1, vcc, 0, v1, vcc
	global_store_dwordx2 v[0:1], v[4:5], off sc1
	v_pk_mul_f32 v[0:1], v[36:37], v[2:3] op_sel_hi:[1,0]
	v_pk_mul_f32 v[4:5], v[38:39], v[2:3] op_sel_hi:[1,0]
	v_cvt_pk_bf16_f32 v0, v0, v1
	v_cvt_pk_bf16_f32 v1, v4, v5
	global_store_dwordx2 v[66:67], v[0:1], off offset:16 sc1
	v_pk_mul_f32 v[0:1], v[40:41], v[2:3] op_sel_hi:[1,0]
	v_pk_mul_f32 v[4:5], v[42:43], v[2:3] op_sel_hi:[1,0]
	v_cvt_pk_bf16_f32 v0, v0, v1
	v_cvt_pk_bf16_f32 v1, v4, v5
	global_store_dwordx2 v[66:67], v[0:1], off offset:32 sc1
	v_pk_mul_f32 v[0:1], v[44:45], v[2:3] op_sel_hi:[1,0]
	v_pk_mul_f32 v[4:5], v[46:47], v[2:3] op_sel_hi:[1,0]
	v_cvt_pk_bf16_f32 v0, v0, v1
	v_cvt_pk_bf16_f32 v1, v4, v5
	global_store_dwordx2 v[66:67], v[0:1], off offset:48 sc1
	v_pk_mul_f32 v[0:1], v[48:49], v[2:3] op_sel_hi:[1,0]
	v_pk_mul_f32 v[4:5], v[50:51], v[2:3] op_sel_hi:[1,0]
	v_cvt_pk_bf16_f32 v0, v0, v1
	v_cvt_pk_bf16_f32 v1, v4, v5
	global_store_dwordx2 v[66:67], v[0:1], off offset:64 sc1
	v_pk_mul_f32 v[0:1], v[52:53], v[2:3] op_sel_hi:[1,0]
	v_pk_mul_f32 v[4:5], v[54:55], v[2:3] op_sel_hi:[1,0]
	v_cvt_pk_bf16_f32 v0, v0, v1
	v_cvt_pk_bf16_f32 v1, v4, v5
	global_store_dwordx2 v[66:67], v[0:1], off offset:80 sc1
	v_pk_mul_f32 v[0:1], v[56:57], v[2:3] op_sel_hi:[1,0]
	v_pk_mul_f32 v[4:5], v[58:59], v[2:3] op_sel_hi:[1,0]
	v_cvt_pk_bf16_f32 v0, v0, v1
	v_cvt_pk_bf16_f32 v1, v4, v5
	global_store_dwordx2 v[66:67], v[0:1], off offset:96 sc1
	v_pk_mul_f32 v[0:1], v[60:61], v[2:3] op_sel_hi:[1,0]
	v_pk_mul_f32 v[2:3], v[62:63], v[2:3] op_sel_hi:[1,0]
	v_cvt_pk_bf16_f32 v0, v0, v1

.LBB0_979:
	s_mov_b64 s[6:7], s[8:9]
	s_add_u32 s6, s6, s2
	s_addc_u32 s7, s7, s3
	s_add_u32 s6, s6, s4
	s_addc_u32 s7, s7, s5
	v_mov_b64_e32 v[66:67], s[6:7]
	s_mov_b64 s[6:7], s[10:11]
	global_load_dword v67, v[66:67], off
	s_add_u32 s6, s6, s2
	s_addc_u32 s7, s7, s3
	s_add_u32 s6, s6, s4
	s_addc_u32 s7, s7, s5
	v_mov_b64_e32 v[70:71], s[6:7]
	s_mov_b64 s[6:7], s[12:13]
	global_load_dword v71, v[70:71], off
	s_add_u32 s6, s6, s2
	s_addc_u32 s7, s7, s3
	s_add_u32 s6, s6, s4
	s_addc_u32 s7, s7, s5
	v_mov_b64_e32 v[72:73], s[6:7]
	s_mov_b64 s[6:7], s[14:15]
	global_load_dword v66, v[72:73], off
	s_add_u32 s6, s6, s2
	s_addc_u32 s7, s7, s3
	s_add_u32 s6, s6, s4
	s_addc_u32 s7, s7, s5
	v_mov_b64_e32 v[72:73], s[6:7]
	global_load_dword v70, v[72:73], off
	s_mov_b64 s[6:7], s[8:9]
	s_add_u32 s6, s6, s2
	s_addc_u32 s7, s7, s3
	s_add_u32 s6, s6, s4
	s_addc_u32 s7, s7, s5
	s_waitcnt vmcnt(0) lgkmcnt(0)
	v_pk_fma_f32 v[66:67], v[66:67], v[70:71], v[68:69]
	v_mov_b64_e32 v[68:69], s[6:7]
	s_mov_b64 s[6:7], s[10:11]
	global_load_dword v69, v[68:69], off offset:4
	s_add_u32 s6, s6, s2
	s_addc_u32 s7, s7, s3
	s_add_u32 s6, s6, s4
	s_addc_u32 s7, s7, s5
	v_mov_b64_e32 v[70:71], s[6:7]
	s_mov_b64 s[6:7], s[12:13]
	global_load_dword v71, v[70:71], off offset:4
	s_add_u32 s6, s6, s2
	s_addc_u32 s7, s7, s3
	s_add_u32 s6, s6, s4
	s_addc_u32 s7, s7, s5
	v_mov_b64_e32 v[72:73], s[6:7]
	s_mov_b64 s[6:7], s[14:15]
	global_load_dword v68, v[72:73], off offset:4
	s_add_u32 s6, s6, s2
	s_addc_u32 s7, s7, s3
	s_add_u32 s6, s6, s4
	s_addc_u32 s7, s7, s5
	v_mov_b64_e32 v[72:73], s[6:7]
	global_load_dword v70, v[72:73], off offset:4
	s_mov_b64 s[6:7], s[8:9]
	s_add_u32 s6, s6, s2
	s_addc_u32 s7, s7, s3
	s_add_u32 s6, s6, s4
	s_addc_u32 s7, s7, s5
	s_waitcnt vmcnt(0) lgkmcnt(0)
	v_pk_fma_f32 v[66:67], v[68:69], v[70:71], v[66:67]
	v_mov_b64_e32 v[68:69], s[6:7]
	s_mov_b64 s[6:7], s[10:11]
	global_load_dword v69, v[68:69], off offset:8
	s_add_u32 s6, s6, s2
	s_addc_u32 s7, s7, s3
	s_add_u32 s6, s6, s4
	s_addc_u32 s7, s7, s5
	v_mov_b64_e32 v[70:71], s[6:7]
	s_mov_b64 s[6:7], s[12:13]
	global_load_dword v71, v[70:71], off offset:8
	s_add_u32 s6, s6, s2
	s_addc_u32 s7, s7, s3
	s_add_u32 s6, s6, s4
	s_addc_u32 s7, s7, s5
	v_mov_b64_e32 v[72:73], s[6:7]
	s_mov_b64 s[6:7], s[14:15]
	global_load_dword v68, v[72:73], off offset:8
	s_add_u32 s6, s6, s2
	s_addc_u32 s7, s7, s3
	s_add_u32 s6, s6, s4
	s_addc_u32 s7, s7, s5
	v_mov_b64_e32 v[72:73], s[6:7]
	global_load_dword v70, v[72:73], off offset:8
	s_mov_b64 s[6:7], s[8:9]
	s_add_u32 s6, s6, s2
	s_addc_u32 s7, s7, s3
	s_add_u32 s6, s6, s4
	s_addc_u32 s7, s7, s5
	s_waitcnt vmcnt(0) lgkmcnt(0)
	v_pk_fma_f32 v[66:67], v[68:69], v[70:71], v[66:67]
	v_mov_b64_e32 v[68:69], s[6:7]
	s_mov_b64 s[6:7], s[10:11]
	global_load_dword v69, v[68:69], off offset:12
	s_add_u32 s6, s6, s2
	s_addc_u32 s7, s7, s3
	s_add_u32 s6, s6, s4
	s_addc_u32 s7, s7, s5
	v_mov_b64_e32 v[70:71], s[6:7]
	s_mov_b64 s[6:7], s[12:13]
	global_load_dword v71, v[70:71], off offset:12
	s_add_u32 s6, s6, s2
	s_addc_u32 s7, s7, s3
	s_add_u32 s6, s6, s4
	s_addc_u32 s7, s7, s5
	v_mov_b64_e32 v[72:73], s[6:7]
	s_mov_b64 s[6:7], s[14:15]
	global_load_dword v68, v[72:73], off offset:12
	s_add_u32 s6, s6, s2
	s_addc_u32 s7, s7, s3
	s_add_u32 s6, s6, s4
	s_addc_u32 s7, s7, s5
	v_mov_b64_e32 v[72:73], s[6:7]
	global_load_dword v70, v[72:73], off offset:12
	s_add_u32 s4, s4, 16
	s_addc_u32 s5, s5, 0
	s_cmpk_lg_i32 s4, 0x80
	s_waitcnt vmcnt(0) lgkmcnt(0)
	v_pk_fma_f32 v[68:69], v[68:69], v[70:71], v[66:67]
	s_cbranch_scc1 .LBB0_979
	v_readlane_b32 s4, v255, 12
	v_mul_f32_e32 v64, 0x3fb8aa3b, v69
	v_rndne_f32_e32 v70, v64
	v_lshl_add_u32 v66, s4, 11, v170
	s_mov_b32 s4, 0x3fb8aa3b
	v_sub_f32_e32 v71, v64, v70
	v_fma_f32 v64, v69, s4, -v64
	v_ashrrev_i32_e32 v67, 31, v66
	v_fmac_f32_e32 v64, 0x32a5705f, v69
	v_lshlrev_b64 v[66:67], 11, v[66:67]
	v_add_f32_e32 v64, v71, v64
	v_lshl_add_u64 v[66:67], s[0:1], 0, v[66:67]
	v_readlane_b32 s0, v255, 13
	v_exp_f32_e32 v64, v64
	v_cvt_i32_f32_e32 v70, v70
	s_lshl_b32 s0, s0, 6
	s_ashr_i32 s1, s0, 31
	v_lshl_add_u64 v[66:67], s[0:1], 1, v[66:67]
	s_mov_b32 s0, 0xc2ce8ed0
	v_ldexp_f32 v64, v64, v70
	v_cmp_ngt_f32_e32 vcc, s0, v69
	s_mov_b32 s1, 0x42b17218
	v_mov_b32_e32 v72, 0x7f800000
	v_cndmask_b32_e32 v64, 0, v64, vcc
	v_cmp_nlt_f32_e32 vcc, s1, v69
	v_mul_f32_e32 v69, 0x3fb8aa3b, v68
	v_rndne_f32_e32 v70, v69
	v_sub_f32_e32 v71, v69, v70
	v_fma_f32 v69, v68, s4, -v69
	v_fmac_f32_e32 v69, 0x32a5705f, v68
	v_add_f32_e32 v69, v71, v69
	v_exp_f32_e32 v69, v69
	v_cvt_i32_f32_e32 v70, v70
	v_cndmask_b32_e32 v64, v72, v64, vcc
	v_cmp_ngt_f32_e32 vcc, s0, v68
	v_readlane_b32 s4, v255, 10
	v_ldexp_f32 v69, v69, v70
	v_cndmask_b32_e32 v69, 0, v69, vcc
	v_cmp_nlt_f32_e32 vcc, s1, v68
	v_readlane_b32 s5, v255, 11
	s_lshl_b64 s[4:5], s[4:5], 2
	v_cndmask_b32_e32 v68, v72, v69, vcc
	v_and_b32_e32 v69, 64, v197
	v_sub_f32_e32 v68, v64, v68
	v_xor_b32_e32 v64, 32, v197
	v_add_u32_e32 v69, 64, v69
	v_cmp_lt_i32_e32 vcc, v64, v69
	v_readlane_b32 s33, v255, 5
	s_nop 0
	v_cndmask_b32_e32 v64, v197, v64, vcc
	v_lshlrev_b32_e32 v73, 2, v64
	ds_bpermute_b32 v64, v73, v182
	s_waitcnt lgkmcnt(0)
	v_add_f32_e32 v64, v182, v64
	v_div_scale_f32 v69, s[0:1], v64, v64, 1.0
	v_rcp_f32_e32 v70, v69
	s_nop 0
	v_fma_f32 v71, -v69, v70, 1.0
	v_fmac_f32_e32 v70, v71, v70
	v_div_scale_f32 v71, vcc, 1.0, v64, 1.0
	v_mul_f32_e32 v72, v71, v70
	v_fma_f32 v74, -v69, v72, v71
	v_fmac_f32_e32 v72, v74, v70
	v_fma_f32 v69, -v69, v72, v71
	v_div_fmas_f32 v69, v69, v70, v72
	v_div_fixup_f32 v72, v69, v64, 1.0
	ds_bpermute_b32 v69, v73, v169
	s_waitcnt lgkmcnt(0)
	v_pk_add_f32 v[68:69], v[168:169], v[68:69]
	s_nop 0
	v_div_scale_f32 v64, s[0:1], v69, v69, v68
	v_rcp_f32_e32 v70, v64
	s_mov_b64 s[0:1], s[16:17]
	s_add_u32 s0, s0, s4
	v_fma_f32 v71, -v64, v70, 1.0
	v_fmac_f32_e32 v70, v71, v70
	v_div_scale_f32 v71, vcc, v68, v69, v68
	v_mul_f32_e32 v74, v71, v70
	v_fma_f32 v75, -v64, v74, v71
	v_fmac_f32_e32 v74, v75, v70
	v_fma_f32 v64, -v64, v74, v71
	v_div_fmas_f32 v64, v64, v70, v74
	v_div_fixup_f32 v74, v64, v69, v68
	v_pk_mul_f32 v[10:11], v[10:11], v[74:75] op_sel_hi:[1,0]
	s_addc_u32 s1, s1, s5
	v_lshlrev_b32_e32 v64, 2, v171
	v_pk_fma_f32 v[26:27], v[26:27], v[72:73], v[10:11] op_sel_hi:[1,0,1] neg_lo:[0,0,1] neg_hi:[0,0,1]
	v_pk_mul_f32 v[10:11], v[12:13], v[74:75] op_sel_hi:[1,0]
	v_lshl_add_u64 v[12:13], s[0:1], 0, v[64:65]
	global_load_dwordx4 v[68:71], v[12:13], off
	v_pk_mul_f32 v[32:33], v[32:33], v[74:75] op_sel_hi:[1,0]
	v_pk_mul_f32 v[34:35], v[34:35], v[74:75] op_sel_hi:[1,0]
	v_pk_fma_f32 v[32:33], v[48:49], v[72:73], v[32:33] op_sel_hi:[1,0,1] neg_lo:[0,0,1] neg_hi:[0,0,1]
	v_pk_fma_f32 v[34:35], v[50:51], v[72:73], v[34:35] op_sel_hi:[1,0,1] neg_lo:[0,0,1] neg_hi:[0,0,1]
	v_pk_mul_f32 v[48:49], v[32:33], v[32:33]
	v_pk_mul_f32 v[50:51], v[34:35], v[34:35]
	v_pk_mul_f32 v[36:37], v[36:37], v[74:75] op_sel_hi:[1,0]
	v_add_f32_e32 v48, v48, v49
	v_pk_fma_f32 v[36:37], v[52:53], v[72:73], v[36:37] op_sel_hi:[1,0,1] neg_lo:[0,0,1] neg_hi:[0,0,1]
	v_add_f32_e32 v48, v50, v48
	v_pk_mul_f32 v[38:39], v[38:39], v[74:75] op_sel_hi:[1,0]
	v_pk_mul_f32 v[52:53], v[36:37], v[36:37]
	v_add_f32_e32 v48, v51, v48
	v_pk_fma_f32 v[38:39], v[54:55], v[72:73], v[38:39] op_sel_hi:[1,0,1] neg_lo:[0,0,1] neg_hi:[0,0,1]
	v_add_f32_e32 v48, v52, v48
	v_pk_mul_f32 v[54:55], v[38:39], v[38:39]
	v_pk_mul_f32 v[40:41], v[40:41], v[74:75] op_sel_hi:[1,0]
	v_add_f32_e32 v48, v53, v48
	v_pk_fma_f32 v[40:41], v[56:57], v[72:73], v[40:41] op_sel_hi:[1,0,1] neg_lo:[0,0,1] neg_hi:[0,0,1]
	v_add_f32_e32 v48, v54, v48
	v_pk_mul_f32 v[42:43], v[42:43], v[74:75] op_sel_hi:[1,0]
	v_pk_mul_f32 v[56:57], v[40:41], v[40:41]
	v_add_f32_e32 v48, v55, v48
	v_pk_fma_f32 v[42:43], v[58:59], v[72:73], v[42:43] op_sel_hi:[1,0,1] neg_lo:[0,0,1] neg_hi:[0,0,1]
	v_add_f32_e32 v48, v56, v48
	v_pk_mul_f32 v[58:59], v[42:43], v[42:43]
	v_pk_mul_f32 v[44:45], v[44:45], v[74:75] op_sel_hi:[1,0]
	v_add_f32_e32 v48, v57, v48
	v_pk_fma_f32 v[44:45], v[60:61], v[72:73], v[44:45] op_sel_hi:[1,0,1] neg_lo:[0,0,1] neg_hi:[0,0,1]
	v_add_f32_e32 v48, v58, v48
	v_pk_mul_f32 v[46:47], v[46:47], v[74:75] op_sel_hi:[1,0]
	v_pk_mul_f32 v[60:61], v[44:45], v[44:45]
	v_add_f32_e32 v48, v59, v48
	v_pk_fma_f32 v[46:47], v[62:63], v[72:73], v[46:47] op_sel_hi:[1,0,1] neg_lo:[0,0,1] neg_hi:[0,0,1]
	v_add_f32_e32 v48, v60, v48
	v_pk_mul_f32 v[62:63], v[46:47], v[46:47]
	v_pk_mul_f32 v[0:1], v[0:1], v[74:75] op_sel_hi:[1,0]
	v_add_f32_e32 v48, v61, v48
	v_pk_fma_f32 v[16:17], v[16:17], v[72:73], v[0:1] op_sel_hi:[1,0,1] neg_lo:[0,0,1] neg_hi:[0,0,1]
	v_add_f32_e32 v48, v62, v48
	v_pk_mul_f32 v[2:3], v[2:3], v[74:75] op_sel_hi:[1,0]
	v_pk_mul_f32 v[0:1], v[16:17], v[16:17]
	v_add_f32_e32 v48, v63, v48
	v_pk_fma_f32 v[18:19], v[18:19], v[72:73], v[2:3] op_sel_hi:[1,0,1] neg_lo:[0,0,1] neg_hi:[0,0,1]
	v_add_f32_e32 v0, v0, v48
	v_pk_mul_f32 v[2:3], v[18:19], v[18:19]
	v_pk_mul_f32 v[4:5], v[4:5], v[74:75] op_sel_hi:[1,0]
	v_add_f32_e32 v0, v1, v0
	v_pk_fma_f32 v[4:5], v[20:21], v[72:73], v[4:5] op_sel_hi:[1,0,1] neg_lo:[0,0,1] neg_hi:[0,0,1]
	v_add_f32_e32 v0, v2, v0
	v_pk_mul_f32 v[6:7], v[6:7], v[74:75] op_sel_hi:[1,0]
	v_pk_mul_f32 v[20:21], v[4:5], v[4:5]
	v_add_f32_e32 v0, v3, v0
	v_pk_fma_f32 v[6:7], v[22:23], v[72:73], v[6:7] op_sel_hi:[1,0,1] neg_lo:[0,0,1] neg_hi:[0,0,1]
	v_add_f32_e32 v0, v20, v0
	v_pk_mul_f32 v[22:23], v[6:7], v[6:7]
	v_pk_mul_f32 v[8:9], v[8:9], v[74:75] op_sel_hi:[1,0]
	v_add_f32_e32 v0, v21, v0
	v_pk_fma_f32 v[8:9], v[24:25], v[72:73], v[8:9] op_sel_hi:[1,0,1] neg_lo:[0,0,1] neg_hi:[0,0,1]
	v_add_f32_e32 v0, v22, v0
	v_pk_mul_f32 v[24:25], v[8:9], v[8:9]
	v_add_f32_e32 v0, v23, v0
	v_add_f32_e32 v0, v24, v0
	v_pk_mul_f32 v[76:77], v[26:27], v[26:27]
	v_add_f32_e32 v0, v25, v0
	v_pk_fma_f32 v[10:11], v[28:29], v[72:73], v[10:11] op_sel_hi:[1,0,1] neg_lo:[0,0,1] neg_hi:[0,0,1]
	v_add_f32_e32 v0, v76, v0
	v_pk_mul_f32 v[28:29], v[10:11], v[10:11]
	v_pk_mul_f32 v[14:15], v[14:15], v[74:75] op_sel_hi:[1,0]
	v_add_f32_e32 v0, v77, v0
	v_pk_fma_f32 v[14:15], v[30:31], v[72:73], v[14:15] op_sel_hi:[1,0,1] neg_lo:[0,0,1] neg_hi:[0,0,1]
	v_add_f32_e32 v0, v28, v0
	v_pk_mul_f32 v[30:31], v[14:15], v[14:15]
	v_add_f32_e32 v0, v29, v0
	v_add_f32_e32 v0, v30, v0
	v_add_f32_e32 v0, v31, v0
	ds_bpermute_b32 v1, v73, v0
	v_lshlrev_b32_e32 v64, 1, v171
	v_lshl_add_u64 v[78:79], v[66:67], 0, v[64:65]
	s_mov_b64 s[0:1], 0x6000300
	v_lshl_add_u64 v[66:67], v[78:79], 0, s[0:1]
	s_waitcnt lgkmcnt(0)
	v_add_f32_e32 v0, v0, v1
	v_fmamk_f32 v0, v0, 0x3c800000, v194
	s_mov_b32 s0, 0xf800000
	v_cmp_gt_f32_e32 vcc, s0, v0
	v_mul_f32_e32 v1, 0x4f800000, v0
	s_nop 0
	v_cndmask_b32_e32 v0, v0, v1, vcc
	v_sqrt_f32_e32 v1, v0
	s_nop 0
	v_add_u32_e32 v2, -1, v1
	v_fma_f32 v3, -v2, v1, v0
	v_cmp_ge_f32_e64 s[0:1], 0, v3
	v_add_u32_e32 v3, 1, v1
	s_nop 0
	v_cndmask_b32_e64 v2, v1, v2, s[0:1]
	v_fma_f32 v1, -v3, v1, v0
	v_cmp_lt_f32_e64 s[0:1], 0, v1
	s_nop 1
	v_cndmask_b32_e64 v1, v2, v3, s[0:1]
	v_mul_f32_e32 v2, 0x37800000, v1
	v_cndmask_b32_e32 v1, v1, v2, vcc
	v_cmp_class_f32_e32 vcc, v0, v195
	s_nop 1
	v_cndmask_b32_e32 v0, v1, v0, vcc
	v_div_scale_f32 v1, s[0:1], v0, v0, v163
	v_rcp_f32_e32 v2, v1
	s_mov_b32 s0, 0x6000000
	v_fma_f32 v3, -v1, v2, 1.0
	v_fmac_f32_e32 v2, v3, v2
	v_div_scale_f32 v3, vcc, v163, v0, v163
	v_mul_f32_e32 v20, v3, v2
	v_fma_f32 v21, -v1, v20, v3
	v_fmac_f32_e32 v20, v21, v2
	v_fma_f32 v1, -v1, v20, v3
	v_div_fmas_f32 v1, v1, v2, v20
	v_div_fixup_f32 v20, v1, v0, v163
	v_pk_mul_f32 v[0:1], v[32:33], v[20:21] op_sel_hi:[1,0]
	v_pk_mul_f32 v[2:3], v[34:35], v[20:21] op_sel_hi:[1,0]
	s_waitcnt vmcnt(0)
	v_pk_mul_f32 v[0:1], v[68:69], v[0:1]
	v_pk_mul_f32 v[2:3], v[70:71], v[2:3]
	v_cvt_pk_bf16_f32 v0, v0, v1
	v_cvt_pk_bf16_f32 v1, v2, v3
	v_add_co_u32_e32 v2, vcc, s0, v78
	v_pk_mul_f32 v[22:23], v[36:37], v[20:21] op_sel_hi:[1,0]
	s_nop 0
	v_addc_co_u32_e32 v3, vcc, 0, v79, vcc
	global_store_dwordx2 v[2:3], v[0:1], off offset:768 sc1
	global_load_dwordx4 v[0:3], v[12:13], off offset:32
	v_pk_mul_f32 v[16:17], v[16:17], v[20:21] op_sel_hi:[1,0]
	v_pk_mul_f32 v[4:5], v[4:5], v[20:21] op_sel_hi:[1,0]
	s_waitcnt vmcnt(0) lgkmcnt(0)
	v_pk_mul_f32 v[0:1], v[0:1], v[22:23]
	v_pk_mul_f32 v[22:23], v[38:39], v[20:21] op_sel_hi:[1,0]
	v_cvt_pk_bf16_f32 v0, v0, v1
	v_pk_mul_f32 v[2:3], v[2:3], v[22:23]
	v_pk_mul_f32 v[22:23], v[40:41], v[20:21] op_sel_hi:[1,0]
	v_cvt_pk_bf16_f32 v1, v2, v3
	global_store_dwordx2 v[66:67], v[0:1], off offset:16 sc1
	global_load_dwordx4 v[0:3], v[12:13], off offset:64
	s_waitcnt vmcnt(0) lgkmcnt(0)
	v_pk_mul_f32 v[0:1], v[0:1], v[22:23]
	v_pk_mul_f32 v[22:23], v[42:43], v[20:21] op_sel_hi:[1,0]
	v_cvt_pk_bf16_f32 v0, v0, v1
	v_pk_mul_f32 v[2:3], v[2:3], v[22:23]
	v_pk_mul_f32 v[22:23], v[44:45], v[20:21] op_sel_hi:[1,0]
	v_cvt_pk_bf16_f32 v1, v2, v3
	global_store_dwordx2 v[66:67], v[0:1], off offset:32 sc1
	global_load_dwordx4 v[0:3], v[12:13], off offset:96
	s_waitcnt vmcnt(0) lgkmcnt(0)
	v_pk_mul_f32 v[0:1], v[0:1], v[22:23]
	v_pk_mul_f32 v[22:23], v[46:47], v[20:21] op_sel_hi:[1,0]
	v_cvt_pk_bf16_f32 v0, v0, v1
	v_pk_mul_f32 v[2:3], v[2:3], v[22:23]
	s_nop 0
	v_cvt_pk_bf16_f32 v1, v2, v3
	global_store_dwordx2 v[66:67], v[0:1], off offset:48 sc1
	global_load_dwordx4 v[0:3], v[12:13], off offset:128
	s_waitcnt vmcnt(0) lgkmcnt(0)
	v_pk_mul_f32 v[0:1], v[0:1], v[16:17]
	v_pk_mul_f32 v[16:17], v[18:19], v[20:21] op_sel_hi:[1,0]
	v_cvt_pk_bf16_f32 v0, v0, v1
	v_pk_mul_f32 v[2:3], v[2:3], v[16:17]
	s_nop 0
	v_cvt_pk_bf16_f32 v1, v2, v3
	global_store_dwordx2 v[66:67], v[0:1], off offset:64 sc1
	global_load_dwordx4 v[0:3], v[12:13], off offset:160
	s_waitcnt vmcnt(0) lgkmcnt(0)
	v_pk_mul_f32 v[0:1], v[0:1], v[4:5]
	v_pk_mul_f32 v[4:5], v[6:7], v[20:21] op_sel_hi:[1,0]
	v_cvt_pk_bf16_f32 v0, v0, v1
	v_pk_mul_f32 v[2:3], v[2:3], v[4:5]
	v_pk_mul_f32 v[4:5], v[8:9], v[20:21] op_sel_hi:[1,0]
	v_cvt_pk_bf16_f32 v1, v2, v3
	global_store_dwordx2 v[66:67], v[0:1], off offset:80 sc1
	global_load_dwordx4 v[0:3], v[12:13], off offset:192
	s_waitcnt vmcnt(0) lgkmcnt(0)
	v_pk_mul_f32 v[0:1], v[0:1], v[4:5]
	v_pk_mul_f32 v[4:5], v[26:27], v[20:21] op_sel_hi:[1,0]
	v_cvt_pk_bf16_f32 v0, v0, v1
	v_pk_mul_f32 v[2:3], v[2:3], v[4:5]
	v_pk_mul_f32 v[4:5], v[10:11], v[20:21] op_sel_hi:[1,0]
	v_cvt_pk_bf16_f32 v1, v2, v3
	global_store_dwordx2 v[66:67], v[0:1], off offset:96 sc1
	global_load_dwordx4 v[0:3], v[12:13], off offset:224
	s_waitcnt vmcnt(0) lgkmcnt(0)
	v_pk_mul_f32 v[0:1], v[0:1], v[4:5]
	v_pk_mul_f32 v[4:5], v[14:15], v[20:21] op_sel_hi:[1,0]
	v_cvt_pk_bf16_f32 v0, v0, v1
	v_pk_mul_f32 v[2:3], v[2:3], v[4:5]
	s_branch .LBB0_898

.LBB0_1006:
	v_readlane_b32 s0, v254, 22
	v_readlane_b32 s4, v252, 0
	s_nop 0
	s_lshr_b32 s0, s0, 2
	s_lshl_b32 s0, s0, 3
	s_lshr_b32 s4, s4, 5
	s_or_b32 s0, s0, s4
	s_lshl_b32 s0, s0, 8
	s_or_b32 s101, s0, 0xff
	s_mov_b32 s0, -1
	v_readlane_b32 s4, v254, 3
	v_mbcnt_lo_u32_b32 v0, s0, 0
	v_mbcnt_hi_u32_b32 v0, s0, v0
	v_readlane_b32 s0, v252, 5
	s_mov_b32 s31, s7
	v_readlane_b32 s36, v254, 24
	v_add_u32_e32 v4, s0, v0
	s_mov_b64 s[0:1], s[40:41]
	s_add_u32 s26, s0, s4
	s_addc_u32 s27, s1, 0
	s_mov_b64 s[0:1], s[40:41]
	s_add_u32 s28, s0, s4
	s_addc_u32 s29, s1, 0
	s_mov_b64 s[4:5], s[40:41]
	v_readfirstlane_b32 s6, v4
	s_add_u32 s34, s4, s7
	v_ashrrev_i32_e32 v6, 3, v4
	s_addc_u32 s35, s5, 0
	s_ashr_i32 s6, s6, 1
	v_ashrrev_i32_e32 v7, 31, v6
	s_and_b32 s7, s6, 0xffffffe0
	v_lshlrev_b64 v[0:1], 7, v[6:7]
	v_lshlrev_b32_e32 v8, 4, v4
	v_and_b32_e32 v5, 31, v4
	s_add_i32 s7, s7, s36
	v_lshl_add_u64 v[2:3], s[28:29], 0, v[0:1]
	v_and_b32_e32 v64, 0x70, v8
	v_or_b32_e32 v172, s7, v5
	v_lshl_add_u64 v[8:9], v[2:3], 0, v[64:65]
	v_lshlrev_b64 v[2:3], 12, v[6:7]
	s_mov_b32 s7, 0xf800000
	v_lshl_add_u64 v[10:11], s[34:35], 0, v[2:3]
	v_add_co_u32_e32 v14, vcc, s7, v8
	v_lshl_add_u64 v[10:11], v[10:11], 0, v[64:65]
	s_mov_b64 s[28:29], 0x11800000
	v_addc_co_u32_e32 v15, vcc, 0, v9, vcc
	s_mov_b32 s7, 0x11800000
	v_lshl_add_u64 v[12:13], v[10:11], 0, s[28:29]
	v_add_co_u32_e32 v10, vcc, s7, v10
	s_mov_b32 s7, 0xf802000
	s_nop 0
	v_addc_co_u32_e32 v11, vcc, 0, v11, vcc
	v_add_co_u32_e32 v8, vcc, s7, v8
	v_ashrrev_i32_e32 v173, 31, v172
	s_nop 0
	v_addc_co_u32_e32 v9, vcc, 0, v9, vcc
	v_bfe_u32 v184, v4, 5, 1
	s_waitcnt vmcnt(0) lgkmcnt(0)
	global_load_dwordx4 v[98:101], v[14:15], off
	global_load_dwordx4 v[106:109], v[10:11], off
	global_load_dwordx4 v[102:105], v[8:9], off
	global_load_dwordx4 v[110:113], v[12:13], off offset:128
	v_lshlrev_b64 v[8:9], 7, v[172:173]
	v_lshl_add_u64 v[8:9], s[26:27], 0, v[8:9]
	v_lshlrev_b32_e32 v170, 4, v184
	v_mov_b32_e32 v171, v65
	v_lshl_add_u64 v[8:9], v[8:9], 0, v[170:171]
	s_mov_b64 s[26:27], 0xf000000
	s_mov_b32 s7, 0xf000000
	v_lshl_add_u64 v[10:11], v[8:9], 0, s[26:27]
	v_add_co_u32_e32 v8, vcc, s7, v8
	s_movk_i32 s7, 0x90
	s_nop 0
	v_addc_co_u32_e32 v9, vcc, 0, v9, vcc
	global_load_dwordx4 v[114:117], v[10:11], off offset:32
	global_load_dwordx4 v[118:121], v[10:11], off offset:64
	global_load_dwordx4 v[122:125], v[8:9], off
	global_load_dwordx4 v[126:129], v[10:11], off offset:96
	v_mad_u64_u32 v[6:7], s[26:27], v6, s7, v[64:65]
	v_readlane_b32 s26, v253, 33
	v_readlane_b32 s27, v253, 34
	v_add_u32_e32 v173, 0, v6
	s_andn2_b64 vcc, exec, s[26:27]
	s_waitcnt vmcnt(0) lgkmcnt(0)
	ds_write_b128 v173, v[98:101]
	ds_write_b128 v173, v[106:109] offset:18432
	s_waitcnt lgkmcnt(0)
	s_barrier
	s_cbranch_vccnz .LBB0_1031
	s_or_b32 s28, s6, 31
	v_readlane_b32 s6, v254, 23
	s_add_u32 s0, s0, s6
	s_addc_u32 s1, s1, 0
	v_lshl_add_u64 v[176:177], s[0:1], 0, v[0:1]
	s_add_u32 s0, s4, s31
	v_mul_u32_u24_e32 v185, 0x90, v5
	v_mad_u32_u24 v5, v5, s7, 0
	v_lshlrev_b32_e32 v6, 2, v184
	v_and_b32_e32 v4, 7, v4
	s_addc_u32 s1, s5, 0
	v_mov_b32_e32 v64, v65
	v_sub_u32_e32 v187, v172, v6
	v_lshlrev_b32_e32 v174, 4, v4
	v_lshl_add_u64 v[178:179], s[0:1], 0, v[2:3]
	v_mov_b32_e32 v66, v65
	v_mov_b32_e32 v67, v65
	v_mov_b32_e32 v68, v65
	v_mov_b32_e32 v69, v65
	v_mov_b32_e32 v70, v65
	v_mov_b32_e32 v71, v65
	v_mov_b32_e32 v72, v65
	v_mov_b32_e32 v73, v65
	v_mov_b32_e32 v74, v65
	v_mov_b32_e32 v75, v65
	v_mov_b32_e32 v76, v65
	v_mov_b32_e32 v77, v65
	v_mov_b32_e32 v78, v65
	v_mov_b32_e32 v79, v65
	v_add_u32_e32 v188, v5, v170
	v_mov_b64_e32 v[32:33], v[64:65]
	v_mov_b64_e32 v[48:49], v[64:65]
	v_mov_b64_e32 v[0:1], v[64:65]
	v_mov_b64_e32 v[16:17], v[64:65]
	v_lshl_add_u32 v186, v184, 5, 0
	v_mov_b32_e32 v175, v65
	v_mov_b32_e32 v169, 0
	s_mov_b32 s29, 3
	v_readlane_b32 s31, v254, 25
	v_mov_b32_e32 v171, 0
	v_mov_b64_e32 v[34:35], v[66:67]
	v_mov_b64_e32 v[36:37], v[68:69]
	v_mov_b64_e32 v[38:39], v[70:71]
	v_mov_b64_e32 v[40:41], v[72:73]
	v_mov_b64_e32 v[42:43], v[74:75]
	v_mov_b64_e32 v[44:45], v[76:77]
	v_mov_b64_e32 v[46:47], v[78:79]
	v_mov_b64_e32 v[50:51], v[66:67]
	v_mov_b64_e32 v[52:53], v[68:69]
	v_mov_b64_e32 v[54:55], v[70:71]
	v_mov_b64_e32 v[56:57], v[72:73]
	v_mov_b64_e32 v[58:59], v[74:75]
	v_mov_b64_e32 v[60:61], v[76:77]
	v_mov_b64_e32 v[62:63], v[78:79]
	v_mov_b64_e32 v[2:3], v[66:67]
	v_mov_b64_e32 v[4:5], v[68:69]
	v_mov_b64_e32 v[6:7], v[70:71]
	v_mov_b64_e32 v[8:9], v[72:73]
	v_mov_b64_e32 v[10:11], v[74:75]
	v_mov_b64_e32 v[12:13], v[76:77]
	v_mov_b64_e32 v[14:15], v[78:79]
	v_mov_b64_e32 v[18:19], v[66:67]
	v_mov_b64_e32 v[20:21], v[68:69]
	v_mov_b64_e32 v[22:23], v[70:71]
	v_mov_b64_e32 v[24:25], v[72:73]
	v_mov_b64_e32 v[26:27], v[74:75]
	v_mov_b64_e32 v[28:29], v[76:77]
	v_mov_b64_e32 v[30:31], v[78:79]
	v_readlane_b32 s6, v253, 31
	s_branch .LBB0_1009

.LBB0_1033:
	s_mov_b64 s[6:7], s[8:9]
	s_add_u32 s6, s6, s2
	s_addc_u32 s7, s7, s3
	s_add_u32 s6, s6, s4
	s_addc_u32 s7, s7, s5
	v_mov_b64_e32 v[68:69], s[6:7]
	s_mov_b64 s[6:7], s[10:11]
	global_load_dword v69, v[68:69], off
	s_add_u32 s6, s6, s2
	s_addc_u32 s7, s7, s3
	s_add_u32 s6, s6, s4
	s_addc_u32 s7, s7, s5
	v_mov_b64_e32 v[70:71], s[6:7]
	s_mov_b64 s[6:7], s[12:13]
	global_load_dword v71, v[70:71], off
	s_add_u32 s6, s6, s2
	s_addc_u32 s7, s7, s3
	s_add_u32 s6, s6, s4
	s_addc_u32 s7, s7, s5
	v_mov_b64_e32 v[72:73], s[6:7]
	s_mov_b64 s[6:7], s[14:15]
	global_load_dword v68, v[72:73], off
	s_add_u32 s6, s6, s2
	s_addc_u32 s7, s7, s3
	s_add_u32 s6, s6, s4
	s_addc_u32 s7, s7, s5
	v_mov_b64_e32 v[72:73], s[6:7]
	global_load_dword v70, v[72:73], off
	s_mov_b64 s[6:7], s[8:9]
	s_add_u32 s6, s6, s2
	s_addc_u32 s7, s7, s3
	s_add_u32 s6, s6, s4
	s_addc_u32 s7, s7, s5
	s_waitcnt vmcnt(0) lgkmcnt(0)
	v_pk_fma_f32 v[66:67], v[68:69], v[70:71], v[66:67]
	v_mov_b64_e32 v[68:69], s[6:7]
	s_mov_b64 s[6:7], s[10:11]
	global_load_dword v69, v[68:69], off offset:4
	s_add_u32 s6, s6, s2
	s_addc_u32 s7, s7, s3
	s_add_u32 s6, s6, s4
	s_addc_u32 s7, s7, s5
	v_mov_b64_e32 v[70:71], s[6:7]
	s_mov_b64 s[6:7], s[12:13]
	global_load_dword v71, v[70:71], off offset:4
	s_add_u32 s6, s6, s2
	s_addc_u32 s7, s7, s3
	s_add_u32 s6, s6, s4
	s_addc_u32 s7, s7, s5
	v_mov_b64_e32 v[72:73], s[6:7]
	s_mov_b64 s[6:7], s[14:15]
	global_load_dword v68, v[72:73], off offset:4
	s_add_u32 s6, s6, s2
	s_addc_u32 s7, s7, s3
	s_add_u32 s6, s6, s4
	s_addc_u32 s7, s7, s5
	v_mov_b64_e32 v[72:73], s[6:7]
	global_load_dword v70, v[72:73], off offset:4
	s_mov_b64 s[6:7], s[8:9]
	s_add_u32 s6, s6, s2
	s_addc_u32 s7, s7, s3
	s_add_u32 s6, s6, s4
	s_addc_u32 s7, s7, s5
	s_waitcnt vmcnt(0) lgkmcnt(0)
	v_pk_fma_f32 v[66:67], v[68:69], v[70:71], v[66:67]
	v_mov_b64_e32 v[68:69], s[6:7]
	s_mov_b64 s[6:7], s[10:11]
	global_load_dword v69, v[68:69], off offset:8
	s_add_u32 s6, s6, s2
	s_addc_u32 s7, s7, s3
	s_add_u32 s6, s6, s4
	s_addc_u32 s7, s7, s5
	v_mov_b64_e32 v[70:71], s[6:7]
	s_mov_b64 s[6:7], s[12:13]
	global_load_dword v71, v[70:71], off offset:8
	s_add_u32 s6, s6, s2
	s_addc_u32 s7, s7, s3
	s_add_u32 s6, s6, s4
	s_addc_u32 s7, s7, s5
	v_mov_b64_e32 v[72:73], s[6:7]
	s_mov_b64 s[6:7], s[14:15]
	global_load_dword v68, v[72:73], off offset:8
	s_add_u32 s6, s6, s2
	s_addc_u32 s7, s7, s3
	s_add_u32 s6, s6, s4
	s_addc_u32 s7, s7, s5
	v_mov_b64_e32 v[72:73], s[6:7]
	global_load_dword v70, v[72:73], off offset:8
	s_mov_b64 s[6:7], s[8:9]
	s_add_u32 s6, s6, s2
	s_addc_u32 s7, s7, s3
	s_add_u32 s6, s6, s4
	s_addc_u32 s7, s7, s5
	s_waitcnt vmcnt(0) lgkmcnt(0)
	v_pk_fma_f32 v[66:67], v[68:69], v[70:71], v[66:67]
	v_mov_b64_e32 v[68:69], s[6:7]
	s_mov_b64 s[6:7], s[10:11]
	global_load_dword v69, v[68:69], off offset:12
	s_add_u32 s6, s6, s2
	s_addc_u32 s7, s7, s3
	s_add_u32 s6, s6, s4
	s_addc_u32 s7, s7, s5
	v_mov_b64_e32 v[70:71], s[6:7]
	s_mov_b64 s[6:7], s[12:13]
	global_load_dword v71, v[70:71], off offset:12
	s_add_u32 s6, s6, s2
	s_addc_u32 s7, s7, s3
	s_add_u32 s6, s6, s4
	s_addc_u32 s7, s7, s5
	v_mov_b64_e32 v[72:73], s[6:7]
	s_mov_b64 s[6:7], s[14:15]
	global_load_dword v68, v[72:73], off offset:12
	s_add_u32 s6, s6, s2
	s_addc_u32 s7, s7, s3
	s_add_u32 s6, s6, s4
	s_addc_u32 s7, s7, s5
	v_mov_b64_e32 v[72:73], s[6:7]
	global_load_dword v70, v[72:73], off offset:12
	s_add_u32 s4, s4, 16
	s_addc_u32 s5, s5, 0
	s_cmpk_lg_i32 s4, 0x80
	s_waitcnt vmcnt(0) lgkmcnt(0)
	v_pk_fma_f32 v[66:67], v[68:69], v[70:71], v[66:67]
	s_cbranch_scc1 .LBB0_1033
	v_readlane_b32 s4, v253, 35
	v_mul_f32_e32 v64, 0x3fb8aa3b, v67
	v_rndne_f32_e32 v70, v64
	v_add_u32_e32 v68, s4, v172
	v_ashrrev_i32_e32 v69, 31, v68
	v_lshlrev_b64 v[68:69], 11, v[68:69]
	v_lshl_add_u64 v[68:69], s[0:1], 0, v[68:69]
	v_readlane_b32 s0, v254, 41
	v_readlane_b32 s1, v254, 42
	s_mov_b32 s4, s0
	v_readlane_b32 s0, v254, 43
	v_readlane_b32 s1, v254, 44
	s_mov_b32 s5, s1
	s_mov_b32 s0, s4
	v_lshl_add_u64 v[68:69], v[68:69], 0, s[4:5]
	s_mov_b32 s4, 0x3fb8aa3b
	v_sub_f32_e32 v71, v64, v70
	v_fma_f32 v64, v67, s4, -v64
	v_fmac_f32_e32 v64, 0x32a5705f, v67
	v_add_f32_e32 v64, v71, v64
	v_exp_f32_e32 v64, v64
	v_cvt_i32_f32_e32 v70, v70
	v_writelane_b32 v254, s0, 41
	v_mov_b32_e32 v72, 0x7f800000
	v_and_b32_e32 v192, 64, v197
	v_writelane_b32 v254, s1, 42
	s_mov_b32 s0, 0xc2ce8ed0
	v_ldexp_f32 v64, v64, v70
	v_cmp_ngt_f32_e32 vcc, s0, v67
	s_mov_b32 s1, 0x42b17218
	s_mov_b32 s31, 2
	v_cndmask_b32_e32 v64, 0, v64, vcc
	v_cmp_nlt_f32_e32 vcc, s1, v67
	v_mul_f32_e32 v67, 0x3fb8aa3b, v66
	v_rndne_f32_e32 v70, v67
	v_sub_f32_e32 v71, v67, v70
	v_fma_f32 v67, v66, s4, -v67
	v_fmac_f32_e32 v67, 0x32a5705f, v66
	v_add_f32_e32 v67, v71, v67
	v_exp_f32_e32 v67, v67
	v_cvt_i32_f32_e32 v70, v70
	v_cndmask_b32_e32 v64, v72, v64, vcc
	v_cmp_ngt_f32_e32 vcc, s0, v66
	v_readlane_b32 s4, v255, 10
	v_ldexp_f32 v67, v67, v70
	v_cndmask_b32_e32 v67, 0, v67, vcc
	v_cmp_nlt_f32_e32 vcc, s1, v66
	v_readlane_b32 s5, v255, 11
	s_lshl_b64 s[4:5], s[4:5], 2
	v_cndmask_b32_e32 v66, v72, v67, vcc
	v_sub_f32_e32 v66, v64, v66
	v_xor_b32_e32 v64, 32, v197
	v_add_u32_e32 v67, 64, v192
	v_cmp_lt_i32_e32 vcc, v64, v67
	s_nop 1
	v_cndmask_b32_e32 v64, v197, v64, vcc
	v_lshlrev_b32_e32 v193, 2, v64
	ds_bpermute_b32 v64, v193, v171
	s_waitcnt lgkmcnt(0)
	v_add_f32_e32 v64, v171, v64
	v_div_scale_f32 v67, s[0:1], v64, v64, 1.0
	v_rcp_f32_e32 v70, v67
	v_mov_b32_e32 v171, v65
	v_fma_f32 v71, -v67, v70, 1.0
	v_fmac_f32_e32 v70, v71, v70
	v_div_scale_f32 v71, vcc, 1.0, v64, 1.0
	v_mul_f32_e32 v72, v71, v70
	v_fma_f32 v73, -v67, v72, v71
	v_fmac_f32_e32 v72, v73, v70
	v_fma_f32 v67, -v67, v72, v71
	v_div_fmas_f32 v67, v67, v70, v72
	v_div_fixup_f32 v70, v67, v64, 1.0
	ds_bpermute_b32 v67, v193, v169
	s_waitcnt lgkmcnt(0)
	v_pk_add_f32 v[66:67], v[168:169], v[66:67]
	s_nop 0
	v_div_scale_f32 v64, s[0:1], v67, v67, v66
	v_rcp_f32_e32 v71, v64
	s_mov_b64 s[0:1], s[16:17]
	s_add_u32 s0, s0, s4
	v_fma_f32 v72, -v64, v71, 1.0
	v_fmac_f32_e32 v71, v72, v71
	v_div_scale_f32 v72, vcc, v66, v67, v66
	v_mul_f32_e32 v73, v72, v71
	v_fma_f32 v74, -v64, v73, v72
	v_fmac_f32_e32 v73, v74, v71
	v_fma_f32 v64, -v64, v73, v72
	v_div_fmas_f32 v64, v64, v71, v73
	v_div_fixup_f32 v72, v64, v67, v66
	v_pk_mul_f32 v[42:43], v[42:43], v[72:73] op_sel_hi:[1,0]
	s_addc_u32 s1, s1, s5
	v_pk_fma_f32 v[66:67], v[10:11], v[70:71], v[42:43] op_sel_hi:[1,0,1] neg_lo:[0,0,1] neg_hi:[0,0,1]
	v_pk_mul_f32 v[10:11], v[44:45], v[72:73] op_sel_hi:[1,0]
	v_pk_mul_f32 v[48:49], v[48:49], v[72:73] op_sel_hi:[1,0]
	v_pk_fma_f32 v[42:43], v[12:13], v[70:71], v[10:11] op_sel_hi:[1,0,1] neg_lo:[0,0,1] neg_hi:[0,0,1]
	v_pk_mul_f32 v[10:11], v[46:47], v[72:73] op_sel_hi:[1,0]
	v_pk_mul_f32 v[50:51], v[50:51], v[72:73] op_sel_hi:[1,0]
	v_pk_fma_f32 v[10:11], v[14:15], v[70:71], v[10:11] op_sel_hi:[1,0,1] neg_lo:[0,0,1] neg_hi:[0,0,1]
	v_lshl_add_u64 v[14:15], s[0:1], 0, v[170:171]
	global_load_dwordx4 v[44:47], v[14:15], off
	v_pk_fma_f32 v[16:17], v[16:17], v[70:71], v[48:49] op_sel_hi:[1,0,1] neg_lo:[0,0,1] neg_hi:[0,0,1]
	v_pk_fma_f32 v[18:19], v[18:19], v[70:71], v[50:51] op_sel_hi:[1,0,1] neg_lo:[0,0,1] neg_hi:[0,0,1]
	v_pk_mul_f32 v[48:49], v[16:17], v[16:17]
	v_pk_mul_f32 v[50:51], v[18:19], v[18:19]
	v_pk_mul_f32 v[52:53], v[52:53], v[72:73] op_sel_hi:[1,0]
	v_add_f32_e32 v48, v48, v49
	v_pk_fma_f32 v[20:21], v[20:21], v[70:71], v[52:53] op_sel_hi:[1,0,1] neg_lo:[0,0,1] neg_hi:[0,0,1]
	v_add_f32_e32 v48, v50, v48
	v_pk_mul_f32 v[54:55], v[54:55], v[72:73] op_sel_hi:[1,0]
	v_pk_mul_f32 v[52:53], v[20:21], v[20:21]
	v_add_f32_e32 v48, v51, v48
	v_pk_fma_f32 v[22:23], v[22:23], v[70:71], v[54:55] op_sel_hi:[1,0,1] neg_lo:[0,0,1] neg_hi:[0,0,1]
	v_add_f32_e32 v48, v52, v48
	v_pk_mul_f32 v[54:55], v[22:23], v[22:23]
	v_pk_mul_f32 v[56:57], v[56:57], v[72:73] op_sel_hi:[1,0]
	v_add_f32_e32 v48, v53, v48
	v_pk_fma_f32 v[24:25], v[24:25], v[70:71], v[56:57] op_sel_hi:[1,0,1] neg_lo:[0,0,1] neg_hi:[0,0,1]
	v_add_f32_e32 v48, v54, v48
	v_pk_mul_f32 v[58:59], v[58:59], v[72:73] op_sel_hi:[1,0]
	v_pk_mul_f32 v[56:57], v[24:25], v[24:25]
	v_add_f32_e32 v48, v55, v48
	v_pk_fma_f32 v[26:27], v[26:27], v[70:71], v[58:59] op_sel_hi:[1,0,1] neg_lo:[0,0,1] neg_hi:[0,0,1]
	v_add_f32_e32 v48, v56, v48
	v_pk_mul_f32 v[58:59], v[26:27], v[26:27]
	v_pk_mul_f32 v[60:61], v[60:61], v[72:73] op_sel_hi:[1,0]
	v_add_f32_e32 v48, v57, v48
	v_pk_fma_f32 v[28:29], v[28:29], v[70:71], v[60:61] op_sel_hi:[1,0,1] neg_lo:[0,0,1] neg_hi:[0,0,1]
	v_add_f32_e32 v48, v58, v48
	v_pk_mul_f32 v[62:63], v[62:63], v[72:73] op_sel_hi:[1,0]
	v_pk_mul_f32 v[60:61], v[28:29], v[28:29]
	v_add_f32_e32 v48, v59, v48
	v_pk_fma_f32 v[30:31], v[30:31], v[70:71], v[62:63] op_sel_hi:[1,0,1] neg_lo:[0,0,1] neg_hi:[0,0,1]
	v_add_f32_e32 v48, v60, v48
	v_pk_mul_f32 v[62:63], v[30:31], v[30:31]
	v_pk_mul_f32 v[32:33], v[32:33], v[72:73] op_sel_hi:[1,0]
	v_add_f32_e32 v48, v61, v48
	v_pk_fma_f32 v[32:33], v[0:1], v[70:71], v[32:33] op_sel_hi:[1,0,1] neg_lo:[0,0,1] neg_hi:[0,0,1]
	v_add_f32_e32 v48, v62, v48
	v_pk_mul_f32 v[34:35], v[34:35], v[72:73] op_sel_hi:[1,0]
	v_pk_mul_f32 v[0:1], v[32:33], v[32:33]
	v_add_f32_e32 v48, v63, v48
	v_pk_fma_f32 v[34:35], v[2:3], v[70:71], v[34:35] op_sel_hi:[1,0,1] neg_lo:[0,0,1] neg_hi:[0,0,1]
	v_add_f32_e32 v0, v0, v48
	v_pk_mul_f32 v[2:3], v[34:35], v[34:35]
	v_pk_mul_f32 v[36:37], v[36:37], v[72:73] op_sel_hi:[1,0]
	v_add_f32_e32 v0, v1, v0
	v_pk_fma_f32 v[4:5], v[4:5], v[70:71], v[36:37] op_sel_hi:[1,0,1] neg_lo:[0,0,1] neg_hi:[0,0,1]
	v_add_f32_e32 v0, v2, v0
	v_pk_mul_f32 v[38:39], v[38:39], v[72:73] op_sel_hi:[1,0]
	v_pk_mul_f32 v[36:37], v[4:5], v[4:5]
	v_add_f32_e32 v0, v3, v0
	v_pk_fma_f32 v[6:7], v[6:7], v[70:71], v[38:39] op_sel_hi:[1,0,1] neg_lo:[0,0,1] neg_hi:[0,0,1]
	v_add_f32_e32 v0, v36, v0
	v_pk_mul_f32 v[38:39], v[6:7], v[6:7]
	v_pk_mul_f32 v[40:41], v[40:41], v[72:73] op_sel_hi:[1,0]
	v_add_f32_e32 v0, v37, v0
	v_pk_fma_f32 v[8:9], v[8:9], v[70:71], v[40:41] op_sel_hi:[1,0,1] neg_lo:[0,0,1] neg_hi:[0,0,1]
	v_add_f32_e32 v0, v38, v0
	v_pk_mul_f32 v[40:41], v[8:9], v[8:9]
	v_add_f32_e32 v0, v39, v0
	v_add_f32_e32 v0, v40, v0
	v_pk_mul_f32 v[74:75], v[66:67], v[66:67]
	v_add_f32_e32 v0, v41, v0
	v_add_f32_e32 v0, v74, v0
	v_pk_mul_f32 v[76:77], v[42:43], v[42:43]
	v_add_f32_e32 v0, v75, v0
	v_add_f32_e32 v0, v76, v0
	v_pk_mul_f32 v[78:79], v[10:11], v[10:11]
	v_add_f32_e32 v0, v77, v0
	v_add_f32_e32 v0, v78, v0
	v_add_f32_e32 v0, v79, v0
	ds_bpermute_b32 v1, v193, v0
	v_lshlrev_b32_e32 v64, 3, v184
	v_lshl_add_u64 v[68:69], v[68:69], 0, v[64:65]
	s_mov_b64 s[0:1], 0x6000300
	v_lshl_add_u64 v[12:13], v[68:69], 0, s[0:1]
	s_waitcnt lgkmcnt(0)
	v_add_f32_e32 v0, v0, v1
	v_fmamk_f32 v0, v0, 0x3c800000, v194
	s_mov_b32 s0, 0xf800000
	v_cmp_gt_f32_e32 vcc, s0, v0
	v_mul_f32_e32 v1, 0x4f800000, v0
	s_nop 0
	v_cndmask_b32_e32 v0, v0, v1, vcc
	v_sqrt_f32_e32 v1, v0
	s_nop 0
	v_add_u32_e32 v2, -1, v1
	v_fma_f32 v3, -v2, v1, v0
	v_cmp_ge_f32_e64 s[0:1], 0, v3
	v_add_u32_e32 v3, 1, v1
	s_nop 0
	v_cndmask_b32_e64 v2, v1, v2, s[0:1]
	v_fma_f32 v1, -v3, v1, v0
	v_cmp_lt_f32_e64 s[0:1], 0, v1
	s_nop 1
	v_cndmask_b32_e64 v1, v2, v3, s[0:1]
	v_mul_f32_e32 v2, 0x37800000, v1
	v_cndmask_b32_e32 v1, v1, v2, vcc
	v_cmp_class_f32_e32 vcc, v0, v195
	s_nop 1
	v_cndmask_b32_e32 v0, v1, v0, vcc
	v_div_scale_f32 v1, s[0:1], v0, v0, v163
	v_rcp_f32_e32 v2, v1
	s_mov_b32 s0, 0x6000000
	v_fma_f32 v3, -v1, v2, 1.0
	v_fmac_f32_e32 v2, v3, v2
	v_div_scale_f32 v3, vcc, v163, v0, v163
	v_mul_f32_e32 v36, v3, v2
	v_fma_f32 v37, -v1, v36, v3
	v_fmac_f32_e32 v36, v37, v2
	v_fma_f32 v1, -v1, v36, v3
	v_div_fmas_f32 v1, v1, v2, v36
	v_div_fixup_f32 v36, v1, v0, v163
	v_pk_mul_f32 v[0:1], v[16:17], v[36:37] op_sel_hi:[1,0]
	v_pk_mul_f32 v[2:3], v[18:19], v[36:37] op_sel_hi:[1,0]
	s_waitcnt vmcnt(0)
	v_pk_mul_f32 v[0:1], v[44:45], v[0:1]
	v_pk_mul_f32 v[2:3], v[46:47], v[2:3]
	v_cvt_pk_bf16_f32 v0, v0, v1
	v_cvt_pk_bf16_f32 v1, v2, v3
	v_add_co_u32_e32 v2, vcc, s0, v68
	v_pk_mul_f32 v[16:17], v[20:21], v[36:37] op_sel_hi:[1,0]
	s_nop 0
	v_addc_co_u32_e32 v3, vcc, 0, v69, vcc
	global_store_dwordx2 v[2:3], v[0:1], off offset:768 sc1
	global_load_dwordx4 v[0:3], v[14:15], off offset:32
	v_pk_mul_f32 v[4:5], v[4:5], v[36:37] op_sel_hi:[1,0]
	s_waitcnt vmcnt(0) lgkmcnt(0)
	v_pk_mul_f32 v[0:1], v[0:1], v[16:17]
	v_pk_mul_f32 v[16:17], v[22:23], v[36:37] op_sel_hi:[1,0]
	v_cvt_pk_bf16_f32 v0, v0, v1
	v_pk_mul_f32 v[2:3], v[2:3], v[16:17]
	v_pk_mul_f32 v[16:17], v[24:25], v[36:37] op_sel_hi:[1,0]
	v_cvt_pk_bf16_f32 v1, v2, v3
	global_store_dwordx2 v[12:13], v[0:1], off offset:16 sc1
	global_load_dwordx4 v[0:3], v[14:15], off offset:64
	s_waitcnt vmcnt(0) lgkmcnt(0)
	v_pk_mul_f32 v[0:1], v[0:1], v[16:17]
	v_pk_mul_f32 v[16:17], v[26:27], v[36:37] op_sel_hi:[1,0]
	v_cvt_pk_bf16_f32 v0, v0, v1
	v_pk_mul_f32 v[2:3], v[2:3], v[16:17]
	v_pk_mul_f32 v[16:17], v[28:29], v[36:37] op_sel_hi:[1,0]
	v_cvt_pk_bf16_f32 v1, v2, v3
	global_store_dwordx2 v[12:13], v[0:1], off offset:32 sc1
	global_load_dwordx4 v[0:3], v[14:15], off offset:96
	s_waitcnt vmcnt(0) lgkmcnt(0)
	v_pk_mul_f32 v[0:1], v[0:1], v[16:17]
	v_pk_mul_f32 v[16:17], v[30:31], v[36:37] op_sel_hi:[1,0]
	v_cvt_pk_bf16_f32 v0, v0, v1
	v_pk_mul_f32 v[2:3], v[2:3], v[16:17]
	v_pk_mul_f32 v[16:17], v[32:33], v[36:37] op_sel_hi:[1,0]
	v_cvt_pk_bf16_f32 v1, v2, v3
	global_store_dwordx2 v[12:13], v[0:1], off offset:48 sc1
	global_load_dwordx4 v[0:3], v[14:15], off offset:128
	s_waitcnt vmcnt(0) lgkmcnt(0)
	v_pk_mul_f32 v[0:1], v[0:1], v[16:17]
	v_pk_mul_f32 v[16:17], v[34:35], v[36:37] op_sel_hi:[1,0]
	v_cvt_pk_bf16_f32 v0, v0, v1
	v_pk_mul_f32 v[2:3], v[2:3], v[16:17]
	s_nop 0
	v_cvt_pk_bf16_f32 v1, v2, v3
	global_store_dwordx2 v[12:13], v[0:1], off offset:64 sc1
	global_load_dwordx4 v[0:3], v[14:15], off offset:160
	s_waitcnt vmcnt(0) lgkmcnt(0)
	v_pk_mul_f32 v[0:1], v[0:1], v[4:5]
	v_pk_mul_f32 v[4:5], v[6:7], v[36:37] op_sel_hi:[1,0]
	v_cvt_pk_bf16_f32 v0, v0, v1
	v_pk_mul_f32 v[2:3], v[2:3], v[4:5]
	v_pk_mul_f32 v[4:5], v[8:9], v[36:37] op_sel_hi:[1,0]
	v_cvt_pk_bf16_f32 v1, v2, v3
	global_store_dwordx2 v[12:13], v[0:1], off offset:80 sc1
	global_load_dwordx4 v[0:3], v[14:15], off offset:192
	s_waitcnt vmcnt(0) lgkmcnt(0)
	v_pk_mul_f32 v[0:1], v[0:1], v[4:5]
	v_pk_mul_f32 v[4:5], v[66:67], v[36:37] op_sel_hi:[1,0]
	v_cvt_pk_bf16_f32 v0, v0, v1
	v_pk_mul_f32 v[2:3], v[2:3], v[4:5]
	v_pk_mul_f32 v[4:5], v[42:43], v[36:37] op_sel_hi:[1,0]
	v_cvt_pk_bf16_f32 v1, v2, v3
	global_store_dwordx2 v[12:13], v[0:1], off offset:96 sc1
	global_load_dwordx4 v[0:3], v[14:15], off offset:224
	s_waitcnt vmcnt(0) lgkmcnt(0)
	v_pk_mul_f32 v[0:1], v[0:1], v[4:5]
	v_pk_mul_f32 v[4:5], v[10:11], v[36:37] op_sel_hi:[1,0]
	v_cvt_pk_bf16_f32 v0, v0, v1
	v_pk_mul_f32 v[2:3], v[2:3], v[4:5]
	s_nop 0
	v_cvt_pk_bf16_f32 v1, v2, v3
	global_store_dwordx2 v[12:13], v[0:1], off offset:112 sc1
	s_branch .LBB0_1037
.LBB0_1035:
	v_lshl_add_u32 v32, s67, 11, v130
	v_ashrrev_i32_e32 v33, 31, v32
	s_mov_b64 s[0:1], s[40:41]
	v_lshlrev_b64 v[32:33], 11, v[32:33]
	s_lshl_b32 s26, s66, 7
	v_lshl_add_u64 v[32:33], s[0:1], 0, v[32:33]
	v_lshl_add_u64 v[34:35], v[32:33], 0, s[26:27]
	ds_bpermute_b32 v32, v193, v140
	s_mov_b32 s1, s27
	v_writelane_b32 v254, s0, 43
	v_lshlrev_b32_e32 v64, 1, v131
	v_readlane_b32 s92, v252, 6
	s_waitcnt lgkmcnt(0)
	v_add_f32_e32 v32, v140, v32
	v_writelane_b32 v254, s1, 44
	v_div_scale_f32 v33, s[0:1], v32, v32, 1.0
	v_rcp_f32_e32 v36, v33
	s_mov_b64 s[0:1], 0x6000000
	v_readlane_b32 s93, v252, 7
	v_fma_f32 v37, -v33, v36, 1.0
	v_fmac_f32_e32 v36, v37, v36
	v_div_scale_f32 v37, vcc, 1.0, v32, 1.0
	v_mul_f32_e32 v38, v37, v36
	v_fma_f32 v39, -v33, v38, v37
	v_fmac_f32_e32 v38, v39, v36
	v_fma_f32 v33, -v33, v38, v37
	v_div_fmas_f32 v33, v33, v36, v38
	v_div_fixup_f32 v32, v33, v32, 1.0
	v_lshl_add_u64 v[36:37], v[34:35], 0, v[64:65]
	v_lshl_add_u64 v[34:35], v[36:37], 0, s[0:1]
	v_pk_mul_f32 v[0:1], v[0:1], v[32:33] op_sel_hi:[1,0]
	v_pk_mul_f32 v[2:3], v[2:3], v[32:33] op_sel_hi:[1,0]
	s_mov_b32 s0, 0x6000000
	v_cvt_pk_bf16_f32 v0, v0, v1
	v_cvt_pk_bf16_f32 v1, v2, v3
	v_add_co_u32_e32 v2, vcc, s0, v36
	s_nop 1
	v_addc_co_u32_e32 v3, vcc, 0, v37, vcc
	global_store_dwordx2 v[2:3], v[0:1], off sc1
	v_pk_mul_f32 v[0:1], v[4:5], v[32:33] op_sel_hi:[1,0]
	v_pk_mul_f32 v[2:3], v[6:7], v[32:33] op_sel_hi:[1,0]
	v_cvt_pk_bf16_f32 v0, v0, v1
	v_cvt_pk_bf16_f32 v1, v2, v3
	global_store_dwordx2 v[34:35], v[0:1], off offset:16 sc1
	v_pk_mul_f32 v[0:1], v[8:9], v[32:33] op_sel_hi:[1,0]
	v_pk_mul_f32 v[2:3], v[10:11], v[32:33] op_sel_hi:[1,0]
	v_cvt_pk_bf16_f32 v0, v0, v1
	v_cvt_pk_bf16_f32 v1, v2, v3
	global_store_dwordx2 v[34:35], v[0:1], off offset:32 sc1
	v_pk_mul_f32 v[0:1], v[12:13], v[32:33] op_sel_hi:[1,0]
	v_pk_mul_f32 v[36:37], v[14:15], v[32:33] op_sel_hi:[1,0]
	v_cvt_pk_bf16_f32 v0, v0, v1
.LBB0_1036:
	v_mov_b32_e32 v33, v32
	v_cvt_pk_bf16_f32 v1, v36, v37
	global_store_dwordx2 v[34:35], v[0:1], off offset:48 sc1
	v_pk_mul_f32 v[0:1], v[16:17], v[32:33]
	v_pk_mul_f32 v[2:3], v[18:19], v[32:33]
	v_cvt_pk_bf16_f32 v0, v0, v1
	v_cvt_pk_bf16_f32 v1, v2, v3
	global_store_dwordx2 v[34:35], v[0:1], off offset:64 sc1
	v_pk_mul_f32 v[0:1], v[20:21], v[32:33]
	v_pk_mul_f32 v[2:3], v[22:23], v[32:33]
	v_cvt_pk_bf16_f32 v0, v0, v1
	v_cvt_pk_bf16_f32 v1, v2, v3
	global_store_dwordx2 v[34:35], v[0:1], off offset:80 sc1
	v_pk_mul_f32 v[0:1], v[24:25], v[32:33]
	v_pk_mul_f32 v[2:3], v[26:27], v[32:33]
	v_cvt_pk_bf16_f32 v0, v0, v1
	v_cvt_pk_bf16_f32 v1, v2, v3
	global_store_dwordx2 v[34:35], v[0:1], off offset:96 sc1
	v_pk_mul_f32 v[0:1], v[28:29], v[32:33]
	v_pk_mul_f32 v[2:3], v[30:31], v[32:33]
	v_cvt_pk_bf16_f32 v0, v0, v1
	v_cvt_pk_bf16_f32 v1, v2, v3
	global_store_dwordx2 v[34:35], v[0:1], off offset:112 sc1
	v_sub_co_u32_e64 v0, s[0:1], s31, 1
	s_nop 0
	v_readfirstlane_b32 s31, v0
	s_and_b64 vcc, exec, s[0:1]
	s_cbranch_vccnz .LBB0_1089
.LBB0_1037:
	s_mul_i32 s0, s31, 5
	s_lshr_b32 s0, s30, s0
	s_bfe_u32 s26, s0, 0x30002
	s_lshl_b32 s0, s0, 5
	s_and_b32 s0, s0, 0x60
	v_readlane_b32 s1, v254, 22
	s_or_b32 s4, s0, s1
	s_sub_i32 s1, s4, 48
	s_cmp_gt_u32 s4, 47
	s_cselect_b32 s0, s1, s4
	s_mul_hi_u32 s0, s0, 0xaaaaaaab
	s_lshr_b32 s0, s0, 2
	s_lshl_b32 s0, s0, 3
	s_or_b32 s0, s0, s26
	s_lshl_b32 s0, s0, 8
	s_lshr_b32 s101, s101, 8
	s_or_b32 s101, s101, s0
	s_cmp_gt_u32 s4, 47
	s_mov_b64 s[0:1], -1
	s_cbranch_scc0 .LBB0_1053
	s_add_i32 s5, s96, 1
	s_cmp_eq_u32 s100, s5
	s_cbranch_scc1 .Lidw_skip
	s_mov_b32 s100, s5
	v_readlane_b32 s0, v252, 5
	s_nop 0
	s_cmp_lg_u32 s0, 0
	s_cbranch_scc1 .Lidw_others
	s_add_u32 s0, s40, 0x13503408
	s_addc_u32 s1, s41, 0
	s_lshl_b32 s5, s5, 8
	v_mov_b32_e32 v1, s5
	buffer_inv sc1
	s_mov_b32 s5, 0

.Lidw_skip:
	s_mov_b32 s5, -1
	s_sub_i32 s0, s4, 48
	v_mbcnt_lo_u32_b32 v0, s5, 0
	v_mbcnt_hi_u32_b32 v0, s5, v0
	v_readlane_b32 s5, v252, 5
	s_mul_hi_u32 s1, s0, 0xaaaaaaab
	s_mov_b64 s[6:7], s[40:41]
	v_add_u32_e32 v8, s5, v0
	s_lshr_b32 s1, s1, 2
	s_lshl_b32 s27, s0, 18
	v_readlane_b32 s34, v254, 43
	s_add_u32 s6, s6, s27
	v_readlane_b32 s35, v254, 44
	s_addc_u32 s7, s7, 0
	s_mov_b32 s39, s35
	s_lshl_b32 s38, s1, 17
	s_mov_b64 s[28:29], s[40:41]
	s_lshl_b64 s[34:35], s[38:39], 1
	s_mov_b64 s[36:37], s[40:41]
	s_mul_i32 s38, s1, 0x160000
	s_mov_b32 s43, s39
	s_lshl_b64 s[38:39], s[38:39], 1
	v_readfirstlane_b32 s5, v8
	s_add_u32 s36, s36, s38
	s_addc_u32 s37, s37, s39
	s_ashr_i32 s27, s5, 1
	s_lshl_b32 s33, s26, 8
	s_and_b32 s5, s27, 0xffffffe0
	s_add_i32 s5, s5, s33
	s_lshl_b32 s38, s26, 2
	v_ashrrev_i32_e32 v0, 3, v8
	v_ashrrev_i32_e32 v1, 31, v0
	s_add_u32 s28, s28, s34
	v_lshlrev_b64 v[2:3], 7, v[0:1]
	v_lshlrev_b32_e32 v4, 4, v8
	s_addc_u32 s29, s29, s35
	v_and_b32_e32 v64, 0x70, v4
	v_lshl_add_u64 v[132:133], s[28:29], 0, v[2:3]
	v_lshl_add_u64 v[2:3], v[132:133], 0, v[64:65]
	v_lshlrev_b64 v[4:5], 12, v[0:1]
	s_mov_b32 s28, 0x10c00000
	v_lshl_add_u64 v[134:135], s[36:37], 0, v[4:5]
	v_add_co_u32_e32 v6, vcc, s28, v2
	v_lshl_add_u64 v[4:5], v[134:135], 0, v[64:65]
	s_nop 0
	v_addc_co_u32_e32 v7, vcc, 0, v3, vcc
	s_mov_b32 s28, 0x11a80000
	s_waitcnt vmcnt(0)
	global_load_dwordx4 v[66:69], v[6:7], off
	v_add_co_u32_e32 v6, vcc, s28, v4
	v_and_b32_e32 v9, 31, v8
	s_nop 0
	v_addc_co_u32_e32 v7, vcc, 0, v5, vcc
	global_load_dwordx4 v[70:73], v[6:7], off
	v_or_b32_e32 v6, s5, v9
	s_mov_b32 s5, 0x10c02000
	v_add_co_u32_e32 v2, vcc, s5, v2
	s_mov_b64 s[28:29], 0x11a80000
	s_nop 0
	v_addc_co_u32_e32 v3, vcc, 0, v3, vcc
	v_ashrrev_i32_e32 v7, 31, v6
	v_bfe_u32 v8, v8, 5, 1
	v_lshl_add_u64 v[4:5], v[4:5], 0, s[28:29]
	global_load_dwordx4 v[74:77], v[2:3], off
	global_load_dwordx4 v[78:81], v[4:5], off offset:128
	v_lshlrev_b64 v[2:3], 7, v[6:7]
	v_lshl_add_u64 v[2:3], s[6:7], 0, v[2:3]
	v_lshlrev_b32_e32 v136, 4, v8
	v_mov_b32_e32 v137, v65
	v_lshl_add_u64 v[2:3], v[2:3], 0, v[136:137]
	s_mov_b64 s[6:7], 0x10000000
	s_brev_b32 s5, 8
	v_lshl_add_u64 v[4:5], v[2:3], 0, s[6:7]
	v_add_co_u32_e32 v2, vcc, s5, v2
	v_lshl_add_u32 v138, s1, 11, v6
	s_nop 0
	v_addc_co_u32_e32 v3, vcc, 0, v3, vcc
	v_ashrrev_i32_e32 v139, 31, v138
	global_load_dwordx4 v[82:85], v[4:5], off offset:32
	global_load_dwordx4 v[86:89], v[4:5], off offset:64
	global_load_dwordx4 v[90:93], v[2:3], off
	global_load_dwordx4 v[94:97], v[4:5], off offset:96
	s_mov_b64 s[6:7], s[40:41]
	v_lshlrev_b64 v[2:3], 8, v[138:139]
	s_mov_b32 s5, 0x13000000
	v_lshl_add_u64 v[2:3], s[6:7], 0, v[2:3]
	v_lshl_add_u64 v[2:3], v[2:3], 0, v[136:137]
	s_mov_b64 s[6:7], 0x13000000
	v_lshl_add_u64 v[4:5], v[2:3], 0, s[6:7]
	v_add_co_u32_e32 v2, vcc, s5, v2
	s_movk_i32 s34, 0x90
	s_nop 0
	v_addc_co_u32_e32 v3, vcc, 0, v3, vcc
	global_load_dwordx4 v[98:101], v[4:5], off offset:32
	global_load_dwordx4 v[102:105], v[4:5], off offset:64
	global_load_dwordx4 v[106:109], v[4:5], off offset:160
	global_load_dwordx4 v[110:113], v[4:5], off offset:192
	global_load_dwordx4 v[114:117], v[4:5], off offset:128
	global_load_dwordx4 v[118:121], v[4:5], off offset:96
	global_load_dwordx4 v[122:125], v[2:3], off
	global_load_dwordx4 v[126:129], v[4:5], off offset:224
	v_mad_u64_u32 v[0:1], s[28:29], v0, s34, v[64:65]
	v_mov_b32_e32 v131, 0
	s_mov_b32 s5, 3
	s_add_i32 s6, s38, 4
	v_lshlrev_b32_e32 v130, 2, v8
	v_add_u32_e32 v137, 0, v0
	s_or_b32 s7, s27, 31
	s_or_b32 s27, s38, 3
	v_mul_u32_u24_e32 v140, 0x90, v9
	v_mad_u32_u24 v141, v9, s34, 0
	v_lshl_add_u32 v142, v8, 5, 0
	s_sub_i32 s28, 0, s33
	s_sub_i32 s29, 0, s38
	v_mov_b32_e32 v0, 0
	v_mov_b32_e32 v1, v131
	v_mov_b32_e32 v2, v131
	v_mov_b32_e32 v3, v131
	v_mov_b32_e32 v4, v131
	v_mov_b32_e32 v5, v131
	v_mov_b32_e32 v6, v131
	v_mov_b32_e32 v7, v131
	v_mov_b32_e32 v8, v131
	v_mov_b32_e32 v9, v131
	v_mov_b32_e32 v10, v131
	v_mov_b32_e32 v11, v131
	v_mov_b32_e32 v12, v131
	v_mov_b32_e32 v13, v131
	v_mov_b32_e32 v14, v131
	v_mov_b32_e32 v15, v131
	v_mov_b32_e32 v16, v131
	v_mov_b32_e32 v17, v131
	v_mov_b32_e32 v18, v131
	v_mov_b32_e32 v19, v131
	v_mov_b32_e32 v20, v131
	v_mov_b32_e32 v21, v131
	v_mov_b32_e32 v22, v131
	v_mov_b32_e32 v23, v131
	v_mov_b32_e32 v24, v131
	v_mov_b32_e32 v25, v131
	v_mov_b32_e32 v26, v131
	v_mov_b32_e32 v27, v131
	v_mov_b32_e32 v28, v131
	v_mov_b32_e32 v29, v131
	v_mov_b32_e32 v30, v131
	v_mov_b32_e32 v31, v131
	s_waitcnt vmcnt(0) lgkmcnt(0)
	ds_write_b128 v137, v[66:69]
	ds_write_b128 v137, v[70:73] offset:18432
	s_waitcnt lgkmcnt(0)
	s_barrier
	v_readlane_b32 s33, v252, 5
	s_nop 0
	s_cmp_lg_u32 s33, 0
	s_cbranch_scc1 .Lsig_skipD
	s_and_b32 s34, s101, 0xff
	s_cmp_eq_u32 s34, 0xff
	s_cbranch_scc1 .Lsig_skipD
	s_lshr_b32 s35, s34, 3
	s_lshl_b32 s35, s35, 8
	s_and_b32 s34, s34, 7
	s_lshl_b32 s34, s34, 2
	s_add_u32 s34, s34, s35
	s_add_u32 s34, s34, 0x13502420
	s_add_u32 s34, s40, s34
	s_addc_u32 s35, s41, 0
	v_mov_b32_e32 v32, 1
	s_mov_b64 exec, 1
	global_atomic_add v65, v32, s[34:35]
	s_mov_b64 exec, -1
	s_nop 0
.Lsig_skipD:
	s_branch .LBB0_1040
.LBB0_1039:
	s_add_i32 s5, s5, 2
	s_addk_i32 s28, 0x80
	v_lshl_add_u64 v[132:133], v[132:133], 0, s[82:83]
	s_cmp_lt_u32 s33, s6
	v_lshl_add_u64 v[134:135], v[134:135], 0, s[80:81]
	s_waitcnt lgkmcnt(0)
	s_barrier
	s_cbranch_scc0 .LBB0_1052

.LBB0_1052:
	s_mul_i32 s1, s1, 6
	s_sub_i32 s5, s0, s1
	s_mov_b64 s[0:1], s[40:41]
	v_lshlrev_b64 v[32:33], 11, v[138:139]
	s_lshl_b32 s42, s5, 7
	v_lshl_add_u64 v[32:33], s[0:1], 0, v[32:33]
	v_lshl_add_u64 v[34:35], v[32:33], 0, s[42:43]
	ds_bpermute_b32 v32, v193, v131
	s_mov_b32 s1, s43
	v_writelane_b32 v254, s0, 43
	v_lshlrev_b32_e32 v64, 1, v130
	v_readlane_b32 s33, v255, 5
	s_waitcnt lgkmcnt(0)
	v_add_f32_e32 v32, v131, v32
	v_writelane_b32 v254, s1, 44
	v_div_scale_f32 v33, s[0:1], v32, v32, 1.0
	v_rcp_f32_e32 v36, v33
	s_mov_b64 s[0:1], 0x6000500
	v_fma_f32 v37, -v33, v36, 1.0
	v_fmac_f32_e32 v36, v37, v36
	v_div_scale_f32 v37, vcc, 1.0, v32, 1.0
	v_mul_f32_e32 v38, v37, v36
	v_fma_f32 v39, -v33, v38, v37
	v_fmac_f32_e32 v38, v39, v36
	v_fma_f32 v33, -v33, v38, v37
	v_div_fmas_f32 v33, v33, v36, v38
	v_div_fixup_f32 v32, v33, v32, 1.0
	v_lshl_add_u64 v[36:37], v[34:35], 0, v[64:65]
	v_lshl_add_u64 v[34:35], v[36:37], 0, s[0:1]
	v_pk_mul_f32 v[0:1], v[0:1], v[32:33] op_sel_hi:[1,0]
	v_pk_mul_f32 v[2:3], v[2:3], v[32:33] op_sel_hi:[1,0]
	s_mov_b32 s0, 0x6000000
	v_cvt_pk_bf16_f32 v0, v0, v1
	v_cvt_pk_bf16_f32 v1, v2, v3
	v_add_co_u32_e32 v2, vcc, s0, v36
	s_mov_b64 s[0:1], 0
	s_nop 0
	v_addc_co_u32_e32 v3, vcc, 0, v37, vcc
	global_store_dwordx2 v[2:3], v[0:1], off offset:1280 sc1
	v_pk_mul_f32 v[0:1], v[4:5], v[32:33] op_sel_hi:[1,0]
	v_pk_mul_f32 v[2:3], v[6:7], v[32:33] op_sel_hi:[1,0]
	v_cvt_pk_bf16_f32 v0, v0, v1
	v_cvt_pk_bf16_f32 v1, v2, v3
	global_store_dwordx2 v[34:35], v[0:1], off offset:16 sc1
	v_pk_mul_f32 v[0:1], v[8:9], v[32:33] op_sel_hi:[1,0]
	v_pk_mul_f32 v[2:3], v[10:11], v[32:33] op_sel_hi:[1,0]
	v_cvt_pk_bf16_f32 v0, v0, v1
	v_cvt_pk_bf16_f32 v1, v2, v3
	global_store_dwordx2 v[34:35], v[0:1], off offset:32 sc1
	v_pk_mul_f32 v[0:1], v[12:13], v[32:33] op_sel_hi:[1,0]
	v_pk_mul_f32 v[36:37], v[14:15], v[32:33] op_sel_hi:[1,0]
	v_cvt_pk_bf16_f32 v0, v0, v1

.LBB0_1055:
	v_subrev_u32_e32 v13, s6, v197
	v_cmp_lt_i32_e32 vcc, v13, v192
	s_nop 1
	v_cndmask_b32_e32 v13, v13, v197, vcc
	v_lshlrev_b32_e32 v13, 2, v13
	ds_bpermute_b32 v13, v13, v9
	v_cmp_gt_i32_e32 vcc, s6, v11
	s_lshl_b32 s6, s6, 1
	s_cmp_gt_i32 s6, 63
	s_waitcnt lgkmcnt(0)
	v_add_f32_e32 v13, v9, v13
	v_cndmask_b32_e32 v9, v13, v9, vcc
	s_cbranch_scc0 .LBB0_1055
	v_cmp_eq_u32_e32 vcc, 63, v11
	s_and_saveexec_b64 s[6:7], vcc
	s_movk_i32 s38, 0x90
	s_mov_b32 s75, 0x9000
	s_lshl_b32 s36, s35, 2
	s_add_i32 s36, s36, 0
	s_add_i32 s36, s36, 0x13800
	v_mov_b32_e32 v11, s36
	ds_write_b32 v11, v9
	s_or_b64 exec, exec, s[6:7]
	s_cmp_lt_i32 s35, 1
	s_waitcnt lgkmcnt(0)
	s_barrier
	s_cbranch_scc0 .Lsig_skipF
	s_and_b32 s6, s101, 0xff
	s_cmp_eq_u32 s6, 0xff
	s_cbranch_scc1 .Lsig_doneF
	s_lshr_b32 s7, s6, 3
	s_lshl_b32 s7, s7, 8
	s_and_b32 s6, s6, 7
	s_lshl_b32 s6, s6, 2
	s_add_u32 s6, s6, s7
	s_add_u32 s6, s6, 0x13502420
	s_add_u32 s6, s40, s6
	s_addc_u32 s7, s41, 0
	v_mov_b32_e32 v13, 1
	s_mov_b64 exec, 1
	global_atomic_add v65, v13, s[6:7]
	s_mov_b64 exec, -1
	s_nop 0
.Lsig_doneF:
	s_cmp_lt_i32 s35, 1
.Lsig_skipF:
	s_cbranch_scc1 .LBB0_1088
	s_add_i32 s6, 0, 0x13800
	v_mov_b32_e32 v11, s6
	ds_read_b32 v11, v11
	s_waitcnt lgkmcnt(0)
	v_add_f32_e32 v11, 0, v11
	s_cmp_lt_i32 s35, 2
	s_cbranch_scc1 .LBB0_1061

.LBB0_1089:
	s_setprio 0
	v_readlane_b32 s0, v255, 8
	s_add_i32 s26, s0, 5
	s_cmp_ge_i32 s26, s93
	s_cbranch_scc1 .LBB0_1145
	s_waitcnt vmcnt(0)
	v_readlane_b32 s0, v252, 3
	v_readlane_b32 s1, v252, 4
	s_and_b64 vcc, exec, s[0:1]
	s_waitcnt lgkmcnt(0)
	s_barrier
	s_cbranch_vccnz .LBB0_1144
	s_lshr_b32 s4, s101, 8
	s_lshr_b32 s5, s4, 3
	s_lshl_b32 s5, s5, 8
	s_and_b32 s4, s4, 7
	s_lshl_b32 s4, s4, 2
	s_add_u32 s4, s4, s5
	s_add_u32 s4, s4, 0x13502420
	s_add_u32 s4, s40, s4
	s_addc_u32 s5, s41, 0
	v_mov_b32_e32 v1, 1
	s_mov_b64 exec, 1
	global_atomic_add v65, v1, s[4:5]
	buffer_inv sc1
	v_readlane_b32 s4, v252, 0
	s_nop 0
	s_lshr_b32 s5, s4, 3
	s_and_b32 s5, s5, 7
	s_and_b32 s4, s4, 7
	s_lshl_b32 s4, s4, 3
	s_or_b32 s4, s4, s5
	s_lshr_b32 s5, s4, 3
	s_lshl_b32 s5, s5, 8
	s_and_b32 s4, s4, 7
	s_lshl_b32 s4, s4, 2
	s_add_u32 s4, s4, s5
	s_add_u32 s4, s4, 0x13502420
	s_add_u32 s4, s40, s4
	s_addc_u32 s5, s41, 0
	s_add_i32 s6, s96, 1
	s_lshl_b32 s6, s6, 4
	v_mov_b32_e32 v2, s6
	s_mov_b32 s27, 0

.Lah_done:
	s_waitcnt vmcnt(0)
	s_mov_b64 s[0:1], -1
.LBB0_1143:
	s_or_b64 exec, exec, s[0:1]
